# RG-LRU gate stage rewritten: single LDS base with immediate offsets, gate choice folded into a per-wave multiplier
# speedup vs baseline: 1.0152x; 1.0069x over previous
.LBB0_454:
	v_lshlrev_b32_e32 v0, 16, v37
	v_lshlrev_b32_e32 v3, 16, v36
	v_lshlrev_b32_e32 v80, 16, v80
	v_lshlrev_b32_e32 v95, 16, v85
	v_fma_f32 v85, v84, v0, v73
	s_ashr_i32 s10, s27, 6
	v_lshlrev_b32_e32 v36, 16, v76
	v_lshlrev_b32_e32 v90, 16, v77
	v_fmac_f32_e32 v85, v83, v3
	v_fma_f32 v0, v42, v80, v72
	v_and_b32_e32 v2, 63, v93
	v_lshlrev_b32_e32 v37, 16, v40
	v_lshlrev_b32_e32 v40, 16, v78
	v_fmac_f32_e32 v85, v82, v36
	v_fmac_f32_e32 v0, v41, v90
	s_mul_i32 s4, s10, 0x240
	v_lshlrev_b32_e32 v94, 16, v79
	v_lshlrev_b32_e32 v98, 16, v86
	s_lshl_b32 s9, s10, 3
	v_fmac_f32_e32 v85, v43, v37
	v_fmac_f32_e32 v0, v39, v40
	v_or_b32_e32 v77, s4, v2
	v_fma_f32 v86, v84, v3, v73
	v_fmac_f32_e32 v0, v38, v37
	v_cvt_pk_bf16_f32 v76, v85, s0
	v_lshl_add_u32 v77, v77, 1, 0
	s_or_b32 s28, s9, 1
	v_fmac_f32_e32 v86, v83, v36
	v_fma_f32 v3, v42, v94, v72
	ds_write_b16 v77, v76 offset:17920
	v_cvt_pk_bf16_f32 v76, v0, s0
	v_fmac_f32_e32 v86, v82, v37
	v_fmac_f32_e32 v3, v41, v80
	s_mul_i32 s4, s28, 0x48
	ds_write_b16 v77, v76 offset:27136
	v_fmac_f32_e32 v86, v43, v40
	v_fmac_f32_e32 v3, v39, v90
	v_add_u32_e32 v77, s4, v2
	v_fmac_f32_e32 v3, v38, v40
	v_cvt_pk_bf16_f32 v76, v86, s0
	v_lshl_add_u32 v101, v77, 1, 0
	v_lshlrev_b32_e32 v100, 16, v87
	ds_write_b16 v101, v76 offset:17920
	v_cvt_pk_bf16_f32 v76, v3, s0
	v_fma_f32 v87, v84, v36, v73
	ds_write_b16 v101, v76 offset:27136
	v_fmac_f32_e32 v87, v83, v37
	v_fma_f32 v76, v42, v95, v72
	v_lshlrev_b32_e32 v96, 16, v81
	v_lshlrev_b32_e32 v97, 16, v88
	v_fmac_f32_e32 v87, v82, v40
	v_fmac_f32_e32 v76, v41, v94
	v_fma_f32 v88, v84, v37, v73
	v_fmac_f32_e32 v87, v43, v90
	v_fmac_f32_e32 v76, v39, v80
	v_fmac_f32_e32 v88, v83, v40
	v_fma_f32 v77, v42, v96, v72
	v_lshlrev_b32_e32 v99, 16, v89
	v_fmac_f32_e32 v76, v38, v90
	v_cvt_pk_bf16_f32 v36, v87, s0
	v_fmac_f32_e32 v88, v82, v90
	v_fmac_f32_e32 v77, v41, v95
	v_fma_f32 v89, v84, v40, v73
	ds_write_b16 v101, v36 offset:18064
	v_cvt_pk_bf16_f32 v36, v76, s0
	v_fmac_f32_e32 v88, v43, v80
	v_fmac_f32_e32 v77, v39, v94
	v_fmac_f32_e32 v89, v83, v90
	v_fma_f32 v78, v42, v97, v72
	ds_write_b16 v101, v36 offset:27280
	v_fmac_f32_e32 v77, v38, v80
	v_cvt_pk_bf16_f32 v36, v88, s0
	v_fmac_f32_e32 v89, v82, v80
	v_fmac_f32_e32 v78, v41, v96
	v_fma_f32 v90, v84, v90, v73
	ds_write_b16 v101, v36 offset:18208
	v_cvt_pk_bf16_f32 v36, v77, s0
	v_fmac_f32_e32 v89, v43, v94
	v_fmac_f32_e32 v78, v39, v95
	v_fmac_f32_e32 v90, v83, v80
	v_fma_f32 v79, v42, v98, v72
	ds_write_b16 v101, v36 offset:27424
	v_fmac_f32_e32 v78, v38, v94
	v_cvt_pk_bf16_f32 v36, v89, s0
	v_fmac_f32_e32 v90, v82, v94
	v_fmac_f32_e32 v79, v41, v97
	v_fma_f32 v81, v84, v80, v73
	ds_write_b16 v101, v36 offset:18352
	v_cvt_pk_bf16_f32 v36, v78, s0
	v_fmac_f32_e32 v90, v43, v95
	v_fmac_f32_e32 v79, v39, v96
	v_fmac_f32_e32 v81, v83, v94
	v_fma_f32 v80, v42, v99, v72
	ds_write_b16 v101, v36 offset:27568
	v_fmac_f32_e32 v79, v38, v95
	v_cvt_pk_bf16_f32 v36, v90, s0
	v_fmac_f32_e32 v81, v82, v95
	v_fmac_f32_e32 v80, v41, v98
	v_fmac_f32_e32 v73, v84, v94
	ds_write_b16 v101, v36 offset:18496
	v_cvt_pk_bf16_f32 v36, v79, s0
	v_fmac_f32_e32 v81, v43, v96
	v_fmac_f32_e32 v80, v39, v97
	v_fmac_f32_e32 v73, v83, v95
	v_fmac_f32_e32 v72, v42, v100
	ds_write_b16 v101, v36 offset:27712
	v_fmac_f32_e32 v80, v38, v96
	v_cvt_pk_bf16_f32 v36, v81, s0
	v_fmac_f32_e32 v73, v82, v96
	v_fmac_f32_e32 v72, v41, v99
	ds_write_b16 v101, v36 offset:18640
	v_cvt_pk_bf16_f32 v36, v80, s0
	v_fmac_f32_e32 v73, v43, v97
	v_fmac_f32_e32 v72, v39, v98
	ds_write_b16 v101, v36 offset:27856
	v_fmac_f32_e32 v72, v38, v97
	v_cvt_pk_bf16_f32 v36, v73, s0
	ds_write_b16 v101, v36 offset:18784
	v_cvt_pk_bf16_f32 v36, v72, s0
	ds_write_b16 v101, v36 offset:28000
	s_waitcnt lgkmcnt(0)
	v_mul_f32_e32 v36, 0xbfb8aa3b, v92
	v_exp_f32_e32 v36, v36
	s_mov_b32 s4, 0x3cf5c28f
	s_barrier
	v_cmp_ngt_f32_e32 vcc, s4, v36
	s_and_saveexec_b64 s[4:5], vcc
	s_xor_b64 s[4:5], exec, s[4:5]
	v_add_f32_e32 v36, 1.0, v36
	v_log_f32_e32 v36, v36
	s_nop 0
	v_mul_f32_e32 v83, 0x3f317218, v36
	s_andn2_saveexec_b64 s[4:5], s[4:5]
	v_fmamk_f32 v37, v36, 0xbe800000, v212
	v_fma_f32 v37, -v36, v37, 0.5
	v_fma_f32 v37, -v36, v37, 1.0
	v_mul_f32_e32 v83, v36, v37
	s_or_b64 exec, exec, s[4:5]
	v_mul_f32_e32 v36, 0xbfb8aa3b, v91
	v_exp_f32_e32 v36, v36
	s_mov_b32 s4, 0x3cf5c28f
	v_cmp_ngt_f32_e32 vcc, s4, v36
	s_and_saveexec_b64 s[4:5], vcc
	s_xor_b64 s[4:5], exec, s[4:5]
	v_add_f32_e32 v36, 1.0, v36
	v_log_f32_e32 v36, v36
	s_nop 0
	v_mul_f32_e32 v91, 0x3f317218, v36
	s_andn2_saveexec_b64 s[4:5], s[4:5]
	v_fmamk_f32 v37, v36, 0xbe800000, v212
	v_fma_f32 v37, -v36, v37, 0.5
	v_fma_f32 v37, -v36, v37, 1.0
	v_mul_f32_e32 v91, v36, v37
	s_or_b64 exec, exec, s[4:5]
	v_mul_f32_e32 v84, 0xc138aa3b, v83
	v_mul_f32_e32 v83, 0xc138aa3b, v91
	v_and_b32_e32 v92, 15, v93
	v_lshrrev_b32_e32 v94, 4, v2
	v_and_b32_e32 v97, 48, v2
	v_mul_u32_u24_e32 v95, 0x104, v94
	v_mul_u32_u24_e32 v96, 0x90, v92
	s_and_b32 s4, s10, 3
	s_lshl_b32 s4, s4, 4
	v_add_u32_e32 v95, v95, v92
	v_add_u32_e32 v93, v96, v97
	v_add_u32_e32 v95, s4, v95
	s_mov_b32 s5, 0x8e00
	s_cmpk_gt_u32 s27, 0xff
	s_cbranch_scc0 .Llru_gate_a
	v_mov_b32_e32 v84, 1.0
	v_mov_b32_e32 v83, 1.0
	s_mov_b32 s5, 0xcf00
.Llru_gate_a:
	v_lshl_add_u32 v95, v95, 2, s5
	ds_read_b128 v[36:39], v93 offset:17920
	ds_read_b128 v[40:43], v93 offset:17984
	ds_read_b128 v[98:101], v93 offset:27136
	ds_read_b128 v[102:105], v93 offset:27200
	s_waitcnt lgkmcnt(0)
	v_mfma_f32_16x16x32_bf16 v[36:39], v[36:39], v[28:31], 0
	v_mfma_f32_16x16x32_bf16 v[98:101], v[98:101], v[32:35], 0
	v_mfma_f32_16x16x32_bf16 v[36:39], v[40:43], v[20:23], v[36:39]
	v_mfma_f32_16x16x32_bf16 v[98:101], v[102:105], v[24:27], v[98:101]
	s_nop 7
	s_nop 1
	v_add_f32_e32 v36, v75, v36
	v_add_f32_e32 v37, v75, v37
	v_add_f32_e32 v38, v75, v38
	v_add_f32_e32 v39, v75, v39
	v_add_f32_e32 v98, v74, v98
	v_add_f32_e32 v99, v74, v99
	v_add_f32_e32 v100, v74, v100
	v_add_f32_e32 v101, v74, v101
	v_mul_f32_e32 v36, 0xbfb8aa3b, v36
	v_mul_f32_e32 v37, 0xbfb8aa3b, v37
	v_mul_f32_e32 v38, 0xbfb8aa3b, v38
	v_mul_f32_e32 v39, 0xbfb8aa3b, v39
	v_mul_f32_e32 v98, 0xbfb8aa3b, v98
	v_mul_f32_e32 v99, 0xbfb8aa3b, v99
	v_mul_f32_e32 v100, 0xbfb8aa3b, v100
	v_mul_f32_e32 v101, 0xbfb8aa3b, v101
	v_exp_f32_e32 v36, v36
	v_exp_f32_e32 v37, v37
	v_exp_f32_e32 v38, v38
	v_exp_f32_e32 v39, v39
	v_exp_f32_e32 v98, v98
	v_exp_f32_e32 v99, v99
	v_exp_f32_e32 v100, v100
	v_exp_f32_e32 v101, v101
	v_add_f32_e32 v36, 1.0, v36
	v_add_f32_e32 v37, 1.0, v37
	v_add_f32_e32 v38, 1.0, v38
	v_add_f32_e32 v39, 1.0, v39
	v_add_f32_e32 v98, 1.0, v98
	v_add_f32_e32 v99, 1.0, v99
	v_add_f32_e32 v100, 1.0, v100
	v_add_f32_e32 v101, 1.0, v101
	v_rcp_f32_e32 v36, v36
	v_rcp_f32_e32 v37, v37
	v_rcp_f32_e32 v38, v38
	v_rcp_f32_e32 v39, v39
	v_rcp_f32_e32 v98, v98
	v_rcp_f32_e32 v99, v99
	v_rcp_f32_e32 v100, v100
	v_rcp_f32_e32 v101, v101
	v_mul_f32_e32 v36, v84, v36
	v_mul_f32_e32 v37, v84, v37
	v_mul_f32_e32 v38, v84, v38
	v_mul_f32_e32 v39, v84, v39
	v_mul_f32_e32 v98, v83, v98
	v_mul_f32_e32 v99, v83, v99
	v_mul_f32_e32 v100, v83, v100
	v_mul_f32_e32 v101, v83, v101
	ds_write_b32 v95, v36 offset:0
	ds_write_b32 v95, v37 offset:260
	ds_write_b32 v95, v38 offset:520
	ds_write_b32 v95, v39 offset:780
	ds_write_b32 v95, v98 offset:33280
	ds_write_b32 v95, v99 offset:33540
	ds_write_b32 v95, v100 offset:33800
	ds_write_b32 v95, v101 offset:34060
	ds_read_b128 v[36:39], v93 offset:20224
	ds_read_b128 v[40:43], v93 offset:20288
	ds_read_b128 v[98:101], v93 offset:29440
	ds_read_b128 v[102:105], v93 offset:29504
	s_waitcnt lgkmcnt(0)
	v_mfma_f32_16x16x32_bf16 v[36:39], v[36:39], v[28:31], 0
	v_mfma_f32_16x16x32_bf16 v[98:101], v[98:101], v[32:35], 0
	v_mfma_f32_16x16x32_bf16 v[36:39], v[40:43], v[20:23], v[36:39]
	v_mfma_f32_16x16x32_bf16 v[98:101], v[102:105], v[24:27], v[98:101]
	s_nop 7
	s_nop 1
	v_add_f32_e32 v36, v75, v36
	v_add_f32_e32 v37, v75, v37
	v_add_f32_e32 v38, v75, v38
	v_add_f32_e32 v39, v75, v39
	v_add_f32_e32 v98, v74, v98
	v_add_f32_e32 v99, v74, v99
	v_add_f32_e32 v100, v74, v100
	v_add_f32_e32 v101, v74, v101
	v_mul_f32_e32 v36, 0xbfb8aa3b, v36
	v_mul_f32_e32 v37, 0xbfb8aa3b, v37
	v_mul_f32_e32 v38, 0xbfb8aa3b, v38
	v_mul_f32_e32 v39, 0xbfb8aa3b, v39
	v_mul_f32_e32 v98, 0xbfb8aa3b, v98
	v_mul_f32_e32 v99, 0xbfb8aa3b, v99
	v_mul_f32_e32 v100, 0xbfb8aa3b, v100
	v_mul_f32_e32 v101, 0xbfb8aa3b, v101
	v_exp_f32_e32 v36, v36
	v_exp_f32_e32 v37, v37
	v_exp_f32_e32 v38, v38
	v_exp_f32_e32 v39, v39
	v_exp_f32_e32 v98, v98
	v_exp_f32_e32 v99, v99
	v_exp_f32_e32 v100, v100
	v_exp_f32_e32 v101, v101
	v_add_f32_e32 v36, 1.0, v36
	v_add_f32_e32 v37, 1.0, v37
	v_add_f32_e32 v38, 1.0, v38
	v_add_f32_e32 v39, 1.0, v39
	v_add_f32_e32 v98, 1.0, v98
	v_add_f32_e32 v99, 1.0, v99
	v_add_f32_e32 v100, 1.0, v100
	v_add_f32_e32 v101, 1.0, v101
	v_rcp_f32_e32 v36, v36
	v_rcp_f32_e32 v37, v37
	v_rcp_f32_e32 v38, v38
	v_rcp_f32_e32 v39, v39
	v_rcp_f32_e32 v98, v98
	v_rcp_f32_e32 v99, v99
	v_rcp_f32_e32 v100, v100
	v_rcp_f32_e32 v101, v101
	v_mul_f32_e32 v36, v84, v36
	v_mul_f32_e32 v37, v84, v37
	v_mul_f32_e32 v38, v84, v38
	v_mul_f32_e32 v39, v84, v39
	v_mul_f32_e32 v98, v83, v98
	v_mul_f32_e32 v99, v83, v99
	v_mul_f32_e32 v100, v83, v100
	v_mul_f32_e32 v101, v83, v101
	ds_write_b32 v95, v36 offset:4160
	ds_write_b32 v95, v37 offset:4420
	ds_write_b32 v95, v38 offset:4680
	ds_write_b32 v95, v39 offset:4940
	ds_write_b32 v95, v98 offset:37440
	ds_write_b32 v95, v99 offset:37700
	ds_write_b32 v95, v100 offset:37960
	ds_write_b32 v95, v101 offset:38220
	ds_read_b128 v[36:39], v93 offset:22528
	ds_read_b128 v[40:43], v93 offset:22592
	ds_read_b128 v[98:101], v93 offset:31744
	ds_read_b128 v[102:105], v93 offset:31808
	s_waitcnt lgkmcnt(0)
	v_mfma_f32_16x16x32_bf16 v[36:39], v[36:39], v[28:31], 0
	v_mfma_f32_16x16x32_bf16 v[98:101], v[98:101], v[32:35], 0
	v_mfma_f32_16x16x32_bf16 v[36:39], v[40:43], v[20:23], v[36:39]
	v_mfma_f32_16x16x32_bf16 v[98:101], v[102:105], v[24:27], v[98:101]
	s_nop 7
	s_nop 1
	v_add_f32_e32 v36, v75, v36
	v_add_f32_e32 v37, v75, v37
	v_add_f32_e32 v38, v75, v38
	v_add_f32_e32 v39, v75, v39
	v_add_f32_e32 v98, v74, v98
	v_add_f32_e32 v99, v74, v99
	v_add_f32_e32 v100, v74, v100
	v_add_f32_e32 v101, v74, v101
	v_mul_f32_e32 v36, 0xbfb8aa3b, v36
	v_mul_f32_e32 v37, 0xbfb8aa3b, v37
	v_mul_f32_e32 v38, 0xbfb8aa3b, v38
	v_mul_f32_e32 v39, 0xbfb8aa3b, v39
	v_mul_f32_e32 v98, 0xbfb8aa3b, v98
	v_mul_f32_e32 v99, 0xbfb8aa3b, v99
	v_mul_f32_e32 v100, 0xbfb8aa3b, v100
	v_mul_f32_e32 v101, 0xbfb8aa3b, v101
	v_exp_f32_e32 v36, v36
	v_exp_f32_e32 v37, v37
	v_exp_f32_e32 v38, v38
	v_exp_f32_e32 v39, v39
	v_exp_f32_e32 v98, v98
	v_exp_f32_e32 v99, v99
	v_exp_f32_e32 v100, v100
	v_exp_f32_e32 v101, v101
	v_add_f32_e32 v36, 1.0, v36
	v_add_f32_e32 v37, 1.0, v37
	v_add_f32_e32 v38, 1.0, v38
	v_add_f32_e32 v39, 1.0, v39
	v_add_f32_e32 v98, 1.0, v98
	v_add_f32_e32 v99, 1.0, v99
	v_add_f32_e32 v100, 1.0, v100
	v_add_f32_e32 v101, 1.0, v101
	v_rcp_f32_e32 v36, v36
	v_rcp_f32_e32 v37, v37
	v_rcp_f32_e32 v38, v38
	v_rcp_f32_e32 v39, v39
	v_rcp_f32_e32 v98, v98
	v_rcp_f32_e32 v99, v99
	v_rcp_f32_e32 v100, v100
	v_rcp_f32_e32 v101, v101
	v_mul_f32_e32 v36, v84, v36
	v_mul_f32_e32 v37, v84, v37
	v_mul_f32_e32 v38, v84, v38
	v_mul_f32_e32 v39, v84, v39
	v_mul_f32_e32 v98, v83, v98
	v_mul_f32_e32 v99, v83, v99
	v_mul_f32_e32 v100, v83, v100
	v_mul_f32_e32 v101, v83, v101
	ds_write_b32 v95, v36 offset:8320
	ds_write_b32 v95, v37 offset:8580
	ds_write_b32 v95, v38 offset:8840
	ds_write_b32 v95, v39 offset:9100
	ds_write_b32 v95, v98 offset:41600
	ds_write_b32 v95, v99 offset:41860
	ds_write_b32 v95, v100 offset:42120
	ds_write_b32 v95, v101 offset:42380
	ds_read_b128 v[36:39], v93 offset:24832
	ds_read_b128 v[40:43], v93 offset:24896
	ds_read_b128 v[98:101], v93 offset:34048
	ds_read_b128 v[102:105], v93 offset:34112
	s_waitcnt lgkmcnt(0)
	v_mfma_f32_16x16x32_bf16 v[36:39], v[36:39], v[28:31], 0
	v_mfma_f32_16x16x32_bf16 v[98:101], v[98:101], v[32:35], 0
	v_mfma_f32_16x16x32_bf16 v[36:39], v[40:43], v[20:23], v[36:39]
	v_mfma_f32_16x16x32_bf16 v[98:101], v[102:105], v[24:27], v[98:101]
	s_nop 7
	s_nop 1
	v_add_f32_e32 v36, v75, v36
	v_add_f32_e32 v37, v75, v37
	v_add_f32_e32 v38, v75, v38
	v_add_f32_e32 v39, v75, v39
	v_add_f32_e32 v98, v74, v98
	v_add_f32_e32 v99, v74, v99
	v_add_f32_e32 v100, v74, v100
	v_add_f32_e32 v101, v74, v101
	v_mul_f32_e32 v36, 0xbfb8aa3b, v36
	v_mul_f32_e32 v37, 0xbfb8aa3b, v37
	v_mul_f32_e32 v38, 0xbfb8aa3b, v38
	v_mul_f32_e32 v39, 0xbfb8aa3b, v39
	v_mul_f32_e32 v98, 0xbfb8aa3b, v98
	v_mul_f32_e32 v99, 0xbfb8aa3b, v99
	v_mul_f32_e32 v100, 0xbfb8aa3b, v100
	v_mul_f32_e32 v101, 0xbfb8aa3b, v101
	v_exp_f32_e32 v36, v36
	v_exp_f32_e32 v37, v37
	v_exp_f32_e32 v38, v38
	v_exp_f32_e32 v39, v39
	v_exp_f32_e32 v98, v98
	v_exp_f32_e32 v99, v99
	v_exp_f32_e32 v100, v100
	v_exp_f32_e32 v101, v101
	v_add_f32_e32 v36, 1.0, v36
	v_add_f32_e32 v37, 1.0, v37
	v_add_f32_e32 v38, 1.0, v38
	v_add_f32_e32 v39, 1.0, v39
	v_add_f32_e32 v98, 1.0, v98
	v_add_f32_e32 v99, 1.0, v99
	v_add_f32_e32 v100, 1.0, v100
	v_add_f32_e32 v101, 1.0, v101
	v_rcp_f32_e32 v36, v36
	v_rcp_f32_e32 v37, v37
	v_rcp_f32_e32 v38, v38
	v_rcp_f32_e32 v39, v39
	v_rcp_f32_e32 v98, v98
	v_rcp_f32_e32 v99, v99
	v_rcp_f32_e32 v100, v100
	v_rcp_f32_e32 v101, v101
	v_mul_f32_e32 v36, v84, v36
	v_mul_f32_e32 v37, v84, v37
	v_mul_f32_e32 v38, v84, v38
	v_mul_f32_e32 v39, v84, v39
	v_mul_f32_e32 v98, v83, v98
	v_mul_f32_e32 v99, v83, v99
	v_mul_f32_e32 v100, v83, v100
	v_mul_f32_e32 v101, v83, v101
	ds_write_b32 v95, v36 offset:12480
	ds_write_b32 v95, v37 offset:12740
	ds_write_b32 v95, v38 offset:13000
	ds_write_b32 v95, v39 offset:13260
	ds_write_b32 v95, v98 offset:45760
	ds_write_b32 v95, v99 offset:46020
	ds_write_b32 v95, v100 offset:46280
	ds_write_b32 v95, v101 offset:46540
